# gemm_wide: store section (vmcnt waits, sumsq, ds_write) woven into second k-step MFMA stream with packed f32 ops split into scalar f32; ks1 fragment prefetch
# speedup vs baseline: 1.0109x; 1.0109x over previous
; template <int EPI>
; __device__ __forceinline__ void gemm_wide(const WS& ws, const bf16_t* A, int lda, const bf16_t* __restrict__ W, int K, float invK,
;                                           int ntn, int ntiles, int bid) {
;     ...
;     auto issue = [&]() {
;       const int idc = l_id < last_id ? l_id : last_id;
;       int mt, nt; tile_of(idc, ntn, mt, nt);
;       const int arow = mt * 256 + hh * 128 + srow;
;       const bf16_t* akb = A + l_kt * 64 + (tid & 7) * 8;
;       const bf16_t* wp = W + (size_t)(nt * 256 + wrow) * K + l_kt * 64 + (tid5 & 7) * 8;
; #pragma unroll
;       for (int i = 0; i < 4; ++i) {
;         int r = arow + 32 * i; r = r < M_ ? r : M_ - 1;
;         ra[i] = *(const u32x4*)(akb + (size_t)r * lda);
;         rb[i] = *(const u32x4*)(wp + (size_t)i * 64 * K);
;       }
;       if (++l_kt == nk) { l_kt = 0; l_id += G; }
;     };
;     auto store = [&](int buf) {
; #pragma unroll
;       for (int i = 0; i < 4; ++i) {
;         ss[i] += sumsq8(__builtin_bit_cast(bf16x8, ra[i]));
;         *(u32x4*)(As + buf * 16384 + i * 4096 + soff) = ra[i];
;         *(u32x4*)(Bs + buf * 32768 + i * 8192 + woff) = rb[i];
;       }
;       if (++st_kt == nk) {
;         st_kt = 0;
; #pragma unroll
;         for (int i = 0; i < 4; ++i) {
;           float t = ss[i];
;           t += __shfl_xor(t, 1); t += __shfl_xor(t, 2); t += __shfl_xor(t, 4);
;           if ((tid & 7) == 0) rsl[srow + 32 * i] = rsqrtf(t * invK + EPS_);
;           ss[i] = 0.f;
;         }
;       }
;     };
;     auto compute = [&](int buf) {
;       const unsigned char* Ab = As + buf * 16384 + (wn * 64 + lr) * 128;
;       const unsigned char* Bb = Bs + buf * 32768 + (wm * 64 + lr) * 128;
; #pragma unroll
;       for (int ks = 0; ks < 2; ++ks) {
;         if (ks == 1) __builtin_amdgcn_sched_barrier(0);
;         const int sw = ((ks * 4 + lq) ^ (lr & 7)) << 4;
;         bf16x8 xf[4], wf[4];
; #pragma unroll
;         for (int i = 0; i < 4; ++i) { xf[i] = *(const bf16x8*)(Ab + i * 2048 + sw); wf[i] = *(const bf16x8*)(Bb + i * 2048 + sw); }
; #pragma unroll
;         for (int ni = 0; ni < 4; ++ni)
; #pragma unroll
;           for (int ti = 0; ti < 4; ++ti) accA[ni][ti] = MFMA16(wf[ni], xf[ti], accA[ni][ti]);
; #pragma unroll
;         for (int i = 0; i < 4; ++i) wf[i] = *(const bf16x8*)(Bb + 16384 + i * 2048 + sw);
; #pragma unroll
;         for (int ni = 0; ni < 4; ++ni)
.LBB0_1043:
	s_and_b32 s5, s35, 1
	v_lshl_add_u32 v13, s5, 15, v206
	v_add_u32_e32 v134, v13, v207
	ds_read_b128 v[98:101], v134
	v_lshl_add_u32 v226, s5, 14, v205
	v_add_u32_e32 v118, v226, v207
	ds_read_b128 v[102:105], v118
	ds_read_b128 v[110:113], v118 offset:2048
	ds_read_b128 v[106:109], v134 offset:2048
	ds_read_b128 v[178:181], v118 offset:4096
	ds_read_b128 v[182:185], v118 offset:6144
	s_waitcnt lgkmcnt(2)
	v_mfma_f32_16x16x32_bf16 v[142:145], v[106:109], v[102:105], v[142:145]
	v_lshl_add_u32 v118, s7, 8, v201
	v_add_u32_e32 v224, s4, v202
	s_lshl_b32 s4, s65, 6
	v_mfma_f32_16x16x32_bf16 v[158:161], v[98:101], v[102:105], v[158:161]
	v_ashrrev_i32_e32 v119, 31, v118
	s_ashr_i32 s5, s4, 31
	s_lshl_b64 s[4:5], s[4:5], 1
	v_mfma_f32_16x16x32_bf16 v[154:157], v[98:101], v[110:113], v[154:157]
	v_mov_b32_e32 v169, v12
	v_lshl_add_u64 v[220:221], v[162:163], 0, s[4:5]
	s_mov_b32 s3, 0x20000
	s_waitcnt lgkmcnt(1)
	v_mfma_f32_16x16x32_bf16 v[150:153], v[98:101], v[178:181], v[150:153]
	s_mov_b32 s2, 0x20000
	s_waitcnt lgkmcnt(0)
	v_mfma_f32_16x16x32_bf16 v[146:149], v[98:101], v[182:185], v[146:149]
	v_mfma_f32_16x16x32_bf16 v[138:141], v[106:109], v[110:113], v[138:141]
	v_mfma_f32_16x16x32_bf16 v[130:133], v[106:109], v[178:181], v[130:133]
	v_mfma_f32_16x16x32_bf16 v[114:117], v[106:109], v[182:185], v[114:117]
	ds_read_b128 v[98:101], v134 offset:4096
	ds_read_b128 v[106:109], v134 offset:6144
	ds_read_b128 v[122:125], v134 offset:18432
	s_waitcnt lgkmcnt(2)
	v_mfma_f32_16x16x32_bf16 v[94:97], v[98:101], v[102:105], v[94:97]
	v_mfma_f32_16x16x32_bf16 v[90:93], v[98:101], v[110:113], v[90:93]
	v_mfma_f32_16x16x32_bf16 v[86:89], v[98:101], v[178:181], v[86:89]
	v_mfma_f32_16x16x32_bf16 v[82:85], v[98:101], v[182:185], v[82:85]
	ds_read_b128 v[98:101], v134 offset:16384
	s_waitcnt lgkmcnt(2)
	v_mfma_f32_16x16x32_bf16 v[78:81], v[106:109], v[102:105], v[78:81]
	v_mfma_f32_16x16x32_bf16 v[74:77], v[106:109], v[110:113], v[74:77]
	v_mfma_f32_16x16x32_bf16 v[70:73], v[106:109], v[178:181], v[70:73]
	v_mfma_f32_16x16x32_bf16 v[66:69], v[106:109], v[182:185], v[66:69]
	v_lshlrev_b64 v[106:107], 11, v[118:119]
	v_lshl_add_u64 v[106:107], s[48:49], 0, v[106:107]
	v_lshl_add_u64 v[106:107], v[106:107], 0, s[4:5]
	v_min_i32_e32 v108, 0x405f, v224
	v_lshl_add_u64 v[222:223], v[106:107], 0, v[168:169]
	v_min_i32_e32 v106, 0x407f, v224
	v_ashrrev_i32_e32 v109, 31, v108
	s_waitcnt lgkmcnt(0)
	v_mfma_f32_16x16x32_bf16 v[62:65], v[98:101], v[102:105], v[62:65]
	v_ashrrev_i32_e32 v107, 31, v106
	v_lshlrev_b64 v[106:107], 11, v[106:107]
	v_lshl_add_u64 v[106:107], v[220:221], 0, v[106:107]
	v_mfma_f32_16x16x32_bf16 v[58:61], v[98:101], v[110:113], v[58:61]
	global_load_dwordx4 v[126:129], v[222:223], off
	v_mfma_f32_16x16x32_bf16 v[54:57], v[98:101], v[178:181], v[54:57]
	v_mfma_f32_16x16x32_bf16 v[50:53], v[98:101], v[182:185], v[50:53]
	v_lshlrev_b64 v[98:99], 11, v[108:109]
	v_lshl_add_u64 v[98:99], v[220:221], 0, v[98:99]
	v_add_co_u32_e32 v98, vcc, s82, v98
	v_mfma_f32_16x16x32_bf16 v[46:49], v[122:125], v[102:105], v[46:49]
	s_nop 0
	v_addc_co_u32_e32 v99, vcc, 0, v99, vcc
	global_load_dwordx4 v[118:121], v[106:107], off
	s_nop 0
	global_load_dwordx4 v[106:109], v[98:99], off
	ds_read_b128 v[212:215], v134 offset:20480
	ds_read_b128 v[216:219], v134 offset:22528
	v_add_co_u32_e32 v98, vcc, s3, v222
	v_mfma_f32_16x16x32_bf16 v[42:45], v[122:125], v[110:113], v[42:45]
	s_nop 0
	v_addc_co_u32_e32 v99, vcc, 0, v223, vcc
	v_mfma_f32_16x16x32_bf16 v[38:41], v[122:125], v[178:181], v[38:41]
	v_mfma_f32_16x16x32_bf16 v[34:37], v[122:125], v[182:185], v[34:37]
	global_load_dwordx4 v[122:125], v[98:99], off
	v_min_i32_e32 v98, 0x403f, v224
	v_ashrrev_i32_e32 v99, 31, v98
	v_lshlrev_b64 v[98:99], 11, v[98:99]
	v_lshl_add_u64 v[98:99], v[220:221], 0, v[98:99]
	v_add_co_u32_e32 v98, vcc, s3, v98
	v_min_i32_e32 v224, 0x401f, v224
	s_nop 0
	v_addc_co_u32_e32 v99, vcc, 0, v99, vcc
	s_mov_b32 s3, 0x40000
	v_ashrrev_i32_e32 v225, 31, v224
	s_waitcnt lgkmcnt(1)
	v_mfma_f32_16x16x32_bf16 v[30:33], v[212:215], v[102:105], v[30:33]
	v_add_co_u32_e32 v134, vcc, s3, v222
	s_mov_b32 s3, 0x30000
	v_mfma_f32_16x16x32_bf16 v[26:29], v[212:215], v[110:113], v[26:29]
	v_addc_co_u32_e32 v135, vcc, 0, v223, vcc
	global_load_dwordx4 v[98:101], v[98:99], off
	v_mfma_f32_16x16x32_bf16 v[22:25], v[212:215], v[178:181], v[22:25]
	global_load_dwordx4 v[134:137], v[134:135], off
	v_mfma_f32_16x16x32_bf16 v[18:21], v[212:215], v[182:185], v[18:21]
	v_lshlrev_b64 v[212:213], 11, v[224:225]
	v_lshl_add_u64 v[212:213], v[220:221], 0, v[212:213]
	s_waitcnt lgkmcnt(0)
	v_mfma_f32_16x16x32_bf16 v[14:17], v[216:219], v[102:105], v[14:17]
	v_add_co_u32_e32 v102, vcc, s3, v212
	s_mov_b32 s3, 0x60000
	s_nop 0
	v_addc_co_u32_e32 v103, vcc, 0, v213, vcc
	v_mfma_f32_16x16x32_bf16 v[8:11], v[216:219], v[110:113], v[8:11]
	v_add_co_u32_e32 v110, vcc, s3, v222
	global_load_dwordx4 v[102:105], v[102:103], off
	s_nop 0
	v_addc_co_u32_e32 v111, vcc, 0, v223, vcc
	global_load_dwordx4 v[110:113], v[110:111], off
	v_mfma_f32_16x16x32_bf16 v[4:7], v[216:219], v[178:181], v[4:7]
	v_mfma_f32_16x16x32_bf16 v[0:3], v[216:219], v[182:185], v[0:3]
	v_add_u32_e32 v13, v13, v208
	ds_read_b128 v[178:181], v13
	v_add_u32_e32 v169, v226, v208
	ds_read_b128 v[182:185], v169
	ds_read_b128 v[212:215], v169 offset:2048
	ds_read_b128 v[216:219], v169 offset:4096
	ds_read_b128 v[220:223], v169 offset:6144
	ds_read_b128 v[244:247], v13 offset:2048
	ds_read_b128 v[248:251], v13 offset:4096
	ds_read_b128 v[252:255], v13 offset:6144
	s_add_i32 s6, s6, 1
	s_waitcnt lgkmcnt(6)
	v_mfma_f32_16x16x32_bf16 v[158:161], v[178:181], v[182:185], v[158:161]
	s_waitcnt lgkmcnt(5)
; #define MFMA16(a, b, c) __builtin_amdgcn_mfma_f32_16x16x32_bf16((a), (b), (c), 0, 0, 0)
; template <int EPI>
; __device__ __forceinline__ void gemm_wide(const WS& ws, const bf16_t* A, int lda, const bf16_t* __restrict__ W, int K, float invK,
;                                           int ntn, int ntiles, int bid) {
;     ...
;     auto store = [&](int buf) {
; #pragma unroll
;       for (int i = 0; i < 4; ++i) {
;         ss[i] += sumsq8(__builtin_bit_cast(bf16x8, ra[i]));
;         *(u32x4*)(As + buf * 16384 + i * 4096 + soff) = ra[i];
;         *(u32x4*)(Bs + buf * 32768 + i * 8192 + woff) = rb[i];
;       }
;     ...
;       for (int ks = 0; ks < 2; ++ks) {
;         if (ks == 1) __builtin_amdgcn_sched_barrier(0);
;         const int sw = ((ks * 4 + lq) ^ (lr & 7)) << 4;
;         bf16x8 xf[4], wf[4];
; #pragma unroll
;         for (int i = 0; i < 4; ++i) { xf[i] = *(const bf16x8*)(Ab + i * 2048 + sw); wf[i] = *(const bf16x8*)(Bb + i * 2048 + sw); }
; #pragma unroll
;         for (int ni = 0; ni < 4; ++ni)
; #pragma unroll
;           for (int ti = 0; ti < 4; ++ti) accA[ni][ti] = MFMA16(wf[ni], xf[ti], accA[ni][ti]);
; #pragma unroll
;         for (int i = 0; i < 4; ++i) wf[i] = *(const bf16x8*)(Bb + 16384 + i * 2048 + sw);
; #pragma unroll
;         for (int ni = 0; ni < 4; ++ni)
; #pragma unroll
;           for (int ti = 0; ti < 4; ++ti) accB[ni][ti] = MFMA16(wf[ni], xf[ti], accB[ni][ti]);
;       }
	v_mfma_f32_16x16x32_bf16 v[154:157], v[178:181], v[212:215], v[154:157]
	s_waitcnt lgkmcnt(4)
	v_mfma_f32_16x16x32_bf16 v[150:153], v[178:181], v[216:219], v[150:153]
	s_waitcnt lgkmcnt(3)
	v_mfma_f32_16x16x32_bf16 v[146:149], v[178:181], v[220:223], v[146:149]
	ds_read_b128 v[178:181], v13 offset:16384
	s_waitcnt lgkmcnt(3)
	v_mfma_f32_16x16x32_bf16 v[142:145], v[244:247], v[182:185], v[142:145]
	v_mfma_f32_16x16x32_bf16 v[138:141], v[244:247], v[212:215], v[138:141]
	v_mfma_f32_16x16x32_bf16 v[130:133], v[244:247], v[216:219], v[130:133]
	v_mfma_f32_16x16x32_bf16 v[114:117], v[244:247], v[220:223], v[114:117]
	ds_read_b128 v[244:247], v13 offset:18432
	s_waitcnt lgkmcnt(3)
	v_mfma_f32_16x16x32_bf16 v[94:97], v[248:251], v[182:185], v[94:97]
	s_add_i32 s4, s35, 1
	s_and_b32 s4, s4, 1
	v_lshl_add_u32 v242, s4, 14, v203
	v_lshl_add_u32 v243, s4, 15, v204
	v_mfma_f32_16x16x32_bf16 v[90:93], v[248:251], v[212:215], v[90:93]
	s_waitcnt vmcnt(6)
	ds_write_b128 v242, v[118:121]
	ds_write_b128 v243, v[126:129]
	v_and_b32_e32 v129, 0xffff0000, v118
	s_waitcnt vmcnt(5)
	v_and_b32_e32 v128, 0xffff0000, v106
	v_mfma_f32_16x16x32_bf16 v[86:89], v[248:251], v[216:219], v[86:89]
	v_lshlrev_b32_e32 v127, 16, v118
	v_lshlrev_b32_e32 v126, 16, v106
	v_mul_f32_e32 v128, v128, v128
	v_mul_f32_e32 v129, v129, v129
	v_mfma_f32_16x16x32_bf16 v[82:85], v[248:251], v[220:223], v[82:85]
	v_and_b32_e32 v118, 0xffff0000, v107
	v_fma_f32 v126, v126, v126, v128
	v_fma_f32 v127, v127, v127, v129
	v_lshlrev_b32_e32 v129, 16, v119
	ds_read_b128 v[248:251], v13 offset:20480
	s_waitcnt lgkmcnt(5)
	v_mfma_f32_16x16x32_bf16 v[78:81], v[252:255], v[182:185], v[78:81]
	v_lshlrev_b32_e32 v128, 16, v107
	v_fma_f32 v126, v128, v128, v126
	v_fma_f32 v127, v129, v129, v127
	v_and_b32_e32 v119, 0xffff0000, v119
	v_mfma_f32_16x16x32_bf16 v[74:77], v[252:255], v[212:215], v[74:77]
	v_fma_f32 v118, v118, v118, v126
	v_fma_f32 v119, v119, v119, v127
	v_lshlrev_b32_e32 v127, 16, v120
	v_lshlrev_b32_e32 v126, 16, v108
	v_mfma_f32_16x16x32_bf16 v[70:73], v[252:255], v[216:219], v[70:73]
	v_fma_f32 v118, v126, v126, v118
	v_fma_f32 v119, v127, v127, v119
	v_and_b32_e32 v127, 0xffff0000, v120
	v_and_b32_e32 v126, 0xffff0000, v108
	v_mfma_f32_16x16x32_bf16 v[66:69], v[252:255], v[220:223], v[66:69]
	v_fma_f32 v118, v126, v126, v118
	v_fma_f32 v119, v127, v127, v119
	v_lshlrev_b32_e32 v126, 16, v109
	v_and_b32_e32 v120, 0xffff0000, v109
	ds_read_b128 v[252:255], v13 offset:22528
	s_waitcnt lgkmcnt(5)
	v_mfma_f32_16x16x32_bf16 v[62:65], v[178:181], v[182:185], v[62:65]
	ds_write_b128 v242, v[106:109] offset:4096
	s_waitcnt vmcnt(4)
	ds_write_b128 v243, v[122:125] offset:8192
	s_waitcnt vmcnt(3)
	ds_write_b128 v242, v[98:101] offset:8192
	v_mfma_f32_16x16x32_bf16 v[58:61], v[178:181], v[212:215], v[58:61]
	s_waitcnt vmcnt(2)
	ds_write_b128 v243, v[134:137] offset:16384
	v_and_b32_e32 v109, 0xffff0000, v98
	s_waitcnt vmcnt(1)
	v_and_b32_e32 v108, 0xffff0000, v102
	v_mfma_f32_16x16x32_bf16 v[54:57], v[178:181], v[216:219], v[54:57]
	v_lshlrev_b32_e32 v107, 16, v98
	v_lshlrev_b32_e32 v106, 16, v102
	v_mul_f32_e32 v108, v108, v108
	v_mfma_f32_16x16x32_bf16 v[50:53], v[178:181], v[220:223], v[50:53]
	v_mul_f32_e32 v109, v109, v109
	v_and_b32_e32 v98, 0xffff0000, v103
	v_fma_f32 v106, v106, v106, v108
	s_waitcnt lgkmcnt(8)
	v_mfma_f32_16x16x32_bf16 v[46:49], v[244:247], v[182:185], v[46:49]
	v_fma_f32 v107, v107, v107, v109
	v_lshlrev_b32_e32 v109, 16, v99
	v_lshlrev_b32_e32 v108, 16, v103
	v_mfma_f32_16x16x32_bf16 v[42:45], v[244:247], v[212:215], v[42:45]
	v_fma_f32 v106, v108, v108, v106
	v_fma_f32 v107, v109, v109, v107
	v_and_b32_e32 v99, 0xffff0000, v99
	v_mfma_f32_16x16x32_bf16 v[38:41], v[244:247], v[216:219], v[38:41]
	v_fma_f32 v98, v98, v98, v106
	v_fma_f32 v99, v99, v99, v107
	v_lshlrev_b32_e32 v107, 16, v100
	v_mfma_f32_16x16x32_bf16 v[34:37], v[244:247], v[220:223], v[34:37]
	v_lshlrev_b32_e32 v106, 16, v104
	v_fma_f32 v98, v106, v106, v98
	v_fma_f32 v99, v107, v107, v99
	s_waitcnt lgkmcnt(5)
	v_mfma_f32_16x16x32_bf16 v[30:33], v[248:251], v[182:185], v[30:33]
	v_and_b32_e32 v107, 0xffff0000, v100
	v_and_b32_e32 v106, 0xffff0000, v104
	v_lshlrev_b32_e32 v127, 16, v121
	v_mfma_f32_16x16x32_bf16 v[26:29], v[248:251], v[212:215], v[26:29]
	v_fma_f32 v98, v106, v106, v98
	v_fma_f32 v99, v107, v107, v99
	v_lshlrev_b32_e32 v107, 16, v101
	v_mfma_f32_16x16x32_bf16 v[22:25], v[248:251], v[216:219], v[22:25]
	v_lshlrev_b32_e32 v106, 16, v105
	v_fma_f32 v118, v126, v126, v118
	v_fma_f32 v119, v127, v127, v119
	v_mfma_f32_16x16x32_bf16 v[18:21], v[248:251], v[220:223], v[18:21]
	v_and_b32_e32 v121, 0xffff0000, v121
	v_fma_f32 v98, v106, v106, v98
	v_fma_f32 v99, v107, v107, v99
	s_waitcnt lgkmcnt(4)
	v_mfma_f32_16x16x32_bf16 v[14:17], v[252:255], v[182:185], v[14:17]
	v_and_b32_e32 v101, 0xffff0000, v101
	v_and_b32_e32 v100, 0xffff0000, v105
	v_fma_f32 v118, v120, v120, v118
	v_mfma_f32_16x16x32_bf16 v[8:11], v[252:255], v[212:215], v[8:11]
	v_fma_f32 v119, v121, v121, v119
	v_fma_f32 v98, v100, v100, v98
	v_fma_f32 v99, v101, v101, v99
	v_mfma_f32_16x16x32_bf16 v[4:7], v[252:255], v[216:219], v[4:7]
	v_add_f32_e32 v176, v176, v118
	v_add_f32_e32 v177, v177, v119
	v_add_f32_e32 v170, v170, v98
	v_mfma_f32_16x16x32_bf16 v[0:3], v[252:255], v[220:223], v[0:3]
	v_add_f32_e32 v171, v171, v99
	ds_write_b128 v242, v[102:105] offset:12288
	s_waitcnt vmcnt(0)
	ds_write_b128 v243, v[110:113] offset:24576
	s_cmp_lg_u32 s6, 16
	s_cbranch_scc1 .LBB0_1094
	ds_read2_b32 v[180:181], v210 offset1:16
	ds_read2_b32 v[178:179], v210 offset0:32 offset1:48
	s_cmpk_gt_i32 s62, 0x4ff
	s_mov_b64 s[4:5], -1
	s_cbranch_scc0 .LBB0_1047
	s_add_i32 s7, s62, 0xfffffb00
	s_movk_i32 s4, 0x4000
	s_cbranch_execz .LBB0_1048

; template <int EPI>
; __device__ __forceinline__ void gemm_wide(const WS& ws, const bf16_t* A, int lda, const bf16_t* __restrict__ W, int K, float invK,
;                                           int ntn, int ntiles, int bid) {
;     ...
;       if (++st_kt == nk) {
;         st_kt = 0;
; #pragma unroll
;         for (int i = 0; i < 4; ++i) {
;           float t = ss[i];
;           t += __shfl_xor(t, 1); t += __shfl_xor(t, 2); t += __shfl_xor(t, 4);
;           if ((tid & 7) == 0) rsl[srow + 32 * i] = rsqrtf(t * invK + EPS_);
;           ss[i] = 0.f;
;         }
;       }
.LBB0_1094:
	s_add_i32 s35, s35, 1
	s_add_i32 s67, s67, 1
	s_cmp_lg_u32 s67, 16
	s_cbranch_scc1 .LBB0_1038
	v_and_b32_e32 v98, 64, v191
	v_xor_b32_e32 v13, 1, v191
	v_add_u32_e32 v99, 64, v98
	v_cmp_lt_i32_e32 vcc, v13, v99
	v_xor_b32_e32 v98, 2, v191
	v_xor_b32_e32 v102, 4, v191
	v_cndmask_b32_e32 v13, v191, v13, vcc
	v_lshlrev_b32_e32 v13, 2, v13
	ds_bpermute_b32 v100, v13, v177
	v_cmp_lt_i32_e32 vcc, v98, v99
	s_waitcnt lgkmcnt(0)
	v_add_f32_e32 v100, v177, v100
	v_cndmask_b32_e32 v98, v191, v98, vcc
	v_lshlrev_b32_e32 v98, 2, v98
	ds_bpermute_b32 v101, v98, v100
	v_cmp_lt_i32_e32 vcc, v102, v99
	s_waitcnt lgkmcnt(0)
	v_add_f32_e32 v100, v100, v101
	v_cndmask_b32_e32 v99, v191, v102, vcc
	v_lshlrev_b32_e32 v99, 2, v99
	ds_bpermute_b32 v101, v99, v100
	s_and_saveexec_b64 s[4:5], s[40:41]
	s_cbranch_execz .LBB0_1097
	s_waitcnt lgkmcnt(0)
	v_add_f32_e32 v100, v100, v101
	v_fmamk_f32 v100, v100, 0x3a800000, v187
	v_mul_f32_e32 v101, 0x4b800000, v100
	v_cmp_gt_f32_e32 vcc, s33, v100
	s_nop 1
	v_cndmask_b32_e32 v100, v100, v101, vcc
	v_rsq_f32_e32 v100, v100
	s_nop 0
	v_mul_f32_e32 v101, 0x45800000, v100
	v_cndmask_b32_e32 v100, v100, v101, vcc
	ds_write_b32 v211, v100
